# P10 work queue: first item of each workgroup is static (item = blockIdx), counter hands out the rest; removes 256 simultaneous same-address atomics at phase start
# speedup vs baseline: 1.0031x; 1.0005x over previous
.LBB0_1218:
	s_mov_b32 s100, 0
	s_cmp_lt_i32 s44, 11
	s_cselect_b64 s[8:9], -1, 0
	s_and_b64 s[22:23], s[8:9], s[6:7]
	s_andn2_b64 vcc, exec, s[22:23]
	s_cbranch_vccnz .LBB0_1363
	s_add_u32 s3, s42, 0x14804000
	s_addc_u32 s56, s43, 0
	s_add_u32 s57, s42, 0x19004000
	s_addc_u32 s58, s43, 0
	s_add_u32 s59, s42, 0x11804000
	s_addc_u32 s60, s43, 0
	s_add_u32 s61, s42, 0x9004000
	s_addc_u32 s62, s43, 0
	s_add_u32 s63, s42, 0x5004000
	s_addc_u32 s64, s43, 0
	s_add_u32 s65, s42, 0x4944000
	s_addc_u32 s66, s43, 0
	s_add_u32 s67, s42, 0x4a44000
	v_mul_u32_u24_e32 v1, 0x110, v212
	s_addc_u32 s68, s43, 0
	v_add_u32_e32 v0, 0xc800, v215
	s_movk_i32 s70, 0x90
	v_mul_u32_u24_e32 v149, 0x90, v212
	v_add_u32_e32 v146, 0, v214
	v_and_b32_e32 v2, 15, v213
	v_lshlrev_b32_e32 v200, 2, v227
	s_add_i32 s71, 0, 0x20010
	v_lshlrev_b32_e32 v152, 1, v214
	v_add_u32_e32 v214, v215, v1
	v_mbcnt_lo_u32_b32 v1, -1, 0
	v_mov_b32_e32 v145, 0
	v_lshlrev_b32_e32 v147, 4, v228
	s_mov_b32 s25, 0
	s_movk_i32 s69, 0x110
	v_mad_u32_u24 v151, v212, s70, v215
	v_lshl_add_u32 v148, v2, 4, 0
	v_lshlrev_b32_e32 v150, 3, v2
	v_bfe_u32 v199, v213, 4, 2
	v_mul_u32_u24_e32 v201, 0x190, v212
	v_mov_b32_e32 v236, s71
	s_movk_i32 s72, 0x1e00
	s_movk_i32 s73, 0x180
	s_mov_b32 s74, 0x78787879
	s_movk_i32 s75, 0x100
	s_mov_b32 s76, 0x38e38e39
	s_movk_i32 s77, 0x80
	s_add_i32 s78, 0, 0xa400
	s_mov_b64 s[26:27], 0x80
	s_mov_b64 s[28:29], 0x100
	s_mov_b32 s79, 0x41000000
	s_mov_b64 s[30:31], 0x180
	s_mov_b64 s[34:35], 0x1400
	s_movk_i32 s80, 0x1200
	s_mov_b32 s81, 0x51eb851f
	s_mov_b64 s[36:37], 0x48000
	s_add_i32 s83, 0, 0xc400
	v_mbcnt_hi_u32_b32 v237, -1, v1
	v_add_u32_e32 v238, v0, v149
	v_mov_b32_e32 v239, 0xff800000
	s_mov_b32 s84, s2
	s_mov_b64 s[6:7], -1
	s_branch .Lp10_first

.LBB0_1226:
	s_or_b64 exec, exec, s[8:9]
	s_mov_b32 s100, 0
	s_waitcnt vmcnt(0)
	v_readfirstlane_b32 s8, v1
	s_add_u32 s8, s8, s46
	v_mov_b32_e32 v1, s71
	s_nop 0
	v_add_u32_e32 v0, s8, v0
	ds_write_b32 v1, v0
.LBB0_1227:
	s_or_b64 exec, exec, s[6:7]
	s_waitcnt vmcnt(0) lgkmcnt(0)
	s_barrier
	ds_read_b32 v0, v236
	s_mov_b64 s[6:7], -1
	s_waitcnt lgkmcnt(0)
	s_barrier
	v_readfirstlane_b32 s84, v0
.Lp10_first:
	s_cmpk_gt_u32 s84, 0x3ff
	s_cbranch_scc1 .LBB0_1222
	s_cmpk_gt_u32 s84, 0x2ff
	s_cbranch_scc0 .LBB0_1285
	s_add_i32 s6, s84, 0xfffffd00
	s_lshr_b32 s24, s6, 6
	s_lshl_b32 s7, s6, 8
	s_lshl_b64 s[38:39], s[24:25], 12
	s_and_b32 s7, s7, 0xf00
	s_or_b32 s38, s38, s7
	s_mul_hi_u32 s8, s38, 0x1e00
	s_mul_i32 s9, s39, 0x1e00
	s_mul_i32 s7, s38, 0x1e00
	s_add_i32 s8, s8, s9
	s_add_u32 s85, s61, s7
	s_addc_u32 s86, s62, s8
	s_lshl_b32 s6, s6, 3
	s_and_b32 s6, s6, 0x180
	s_lshl_b32 s87, s6, 1
	s_add_u32 s7, s85, s87
	s_addc_u32 s9, s86, 0
	s_add_u32 s8, s7, 0x1000
	s_addc_u32 s9, s9, 0
	s_lshl_b32 s24, s24, 8
	s_lshl_b64 s[10:11], s[24:25], 10
	s_add_u32 s7, s65, s10
	s_addc_u32 s10, s66, s11
	s_add_u32 s50, s7, s87
	v_readfirstlane_b32 s54, v213
	s_addc_u32 s51, s10, 0
	s_lshr_b32 s90, s54, 6
	s_lshl_b32 s82, s90, 5
	v_or_b32_e32 v180, s82, v212
	v_mov_b64_e32 v[0:1], s[8:9]
	v_mad_u64_u32 v[0:1], s[8:9], v180, s72, v[0:1]
	v_mov_b32_e32 v153, v145
	v_lshl_add_u64 v[0:1], v[0:1], 0, v[152:153]
	global_load_dwordx4 v[124:127], v[0:1], off
	global_load_dwordx4 v[120:123], v[0:1], off offset:32
	global_load_dwordx4 v[116:119], v[0:1], off offset:64
	global_load_dwordx4 v[112:115], v[0:1], off offset:96
	global_load_dwordx4 v[108:111], v[0:1], off offset:128
	global_load_dwordx4 v[104:107], v[0:1], off offset:160
	global_load_dwordx4 v[100:103], v[0:1], off offset:192
	global_load_dwordx4 v[96:99], v[0:1], off offset:224
	s_lshl_b32 s88, s90, 10
	v_or_b32_e32 v0, s88, v147
	v_mul_hi_i32 v1, v0, s74
	v_lshrrev_b32_e32 v2, 31, v1
	v_ashrrev_i32_e32 v1, 7, v1
	v_add_u32_e32 v1, v1, v2
	v_mul_i32_i24_e32 v2, 0x110, v1
	v_sub_u32_e32 v2, v0, v2
	v_cmp_gt_i32_e32 vcc, s75, v2
	v_min_i32_e32 v1, 63, v1
	s_cmpk_lt_u32 s54, 0x440
	v_cndmask_b32_e32 v2, 0, v2, vcc
	s_cselect_b64 s[8:9], -1, 0
	s_cmpk_gt_u32 s54, 0x43f
	v_lshl_add_u32 v144, v1, 10, v2
	s_cbranch_scc1 .LBB0_1231
	s_add_i32 m0, s88, 0
	s_nop 0
	global_load_lds_dwordx4 v144, s[50:51]
